# P3c: four lse loads merged into one load + quad-broadcast DPP
# baseline (speedup 1.0000x reference)
.LBB0_462:
	s_or_b64 exec, exec, s[0:1]
	v_readlane_b32 s2, v251, 28
	v_readlane_b32 s3, v251, 29
	s_andn2_b64 vcc, exec, s[2:3]
	s_waitcnt lgkmcnt(0)
	v_cndmask_b32_e64 v0, 0, 1, s[2:3]
	v_cmp_ne_u32_e64 s[0:1], 1, v0
	s_barrier
	s_nop 0
	v_writelane_b32 v250, s0, 33
	s_nop 1
	v_writelane_b32 v250, s1, 34
	s_cbranch_vccnz .LBB0_473
	v_readlane_b32 s0, v251, 47
	v_ashrrev_i32_e32 v4, 2, v168
	v_readlane_b32 s1, v251, 48
	s_mov_b32 s26, s0
	s_ashr_i32 s27, s0, 31
	v_lshlrev_b32_e32 v2, 6, v4
	v_lshlrev_b32_e32 v6, 4, v168
	s_lshl_b64 s[0:1], s[26:27], 11
	v_and_b32_e32 v0, 3, v168
	s_lshl_b64 s[2:3], s[26:27], 10
	v_ashrrev_i32_e32 v5, 31, v4
	v_ashrrev_i32_e32 v3, 31, v2
	v_lshl_or_b32 v0, v0, 5, s0
	v_mov_b32_e32 v1, s1
	s_ashr_i32 s93, s92, 31
	v_and_or_b32 v6, v6, 48, s2
	v_mov_b32_e32 v7, s3
	s_lshl_b64 s[6:7], s[26:27], 6
	s_mov_b32 s8, s26
	v_lshl_add_u64 v[0:1], v[2:3], 1, v[0:1]
	s_lshl_b64 s[0:1], s[92:93], 11
	v_lshl_add_u64 v[2:3], v[6:7], 0, v[2:3]
	s_lshl_b64 s[2:3], s[92:93], 10
	v_lshl_add_u64 v[4:5], v[4:5], 2, s[6:7]
	s_lshl_b64 s[6:7], s[92:93], 6
	v_readlane_b32 s93, v251, 49
	s_mov_b32 s10, 0xff800000
	v_writelane_b32 v251, s8, 47
	s_mov_b32 s11, s26
	s_nop 0
	v_writelane_b32 v251, s9, 48
	v_and_b32_e32 v46, 3, v168
	v_lshlrev_b32_e32 v46, 21, v46
	v_add_u32_e32 v46, 0x1f100000, v46
	v_mov_b32_e32 v47, 0
	s_branch .LBB0_465

.LBB0_465:
	v_lshl_add_u64 v[6:7], s[20:21], 0, v[4:5]
	v_lshl_add_u64 v[8:9], v[6:7], 0, v[46:47]
	global_load_dword v14, v[8:9], off
	v_mov_b32_e32 v16, 0
	v_mov_b32_e32 v17, v16
	v_mov_b64_e32 v[18:19], v[16:17]
	v_mov_b64_e32 v[20:21], v[16:17]
	v_mov_b64_e32 v[6:7], v[16:17]
	v_mov_b64_e32 v[8:9], v[16:17]
	v_mov_b64_e32 v[10:11], v[16:17]
	v_mov_b64_e32 v[12:13], v[16:17]
	v_mov_b64_e32 v[22:23], v[16:17]
	s_waitcnt vmcnt(0)
	v_mov_b32_dpp v27, v14 quad_perm:[1,1,1,1] row_mask:0xf bank_mask:0xf
	v_mov_b32_dpp v26, v14 quad_perm:[2,2,2,2] row_mask:0xf bank_mask:0xf
	v_mov_b32_dpp v24, v14 quad_perm:[3,3,3,3] row_mask:0xf bank_mask:0xf
	v_mov_b32_dpp v14, v14 quad_perm:[0,0,0,0] row_mask:0xf bank_mask:0xf
	v_max3_f32 v15, v14, s10, v27
	s_waitcnt vmcnt(0)
	v_max3_f32 v25, v15, v26, v24
	v_sub_f32_e32 v14, v14, v25
	v_exp_f32_e32 v28, v14
	v_mov_b64_e32 v[14:15], v[16:17]
	v_cmp_lt_f32_e32 vcc, 0, v28
	s_and_saveexec_b64 s[8:9], vcc
	s_cbranch_execz .LBB0_467
	v_lshl_add_u64 v[6:7], s[20:21], 0, v[2:3]
	v_add_co_u32_e32 v6, vcc, 0x13100000, v6
	v_mul_f32_e32 v16, 0x3d800000, v28
	s_nop 0
	v_addc_co_u32_e32 v7, vcc, 0, v7, vcc
	global_load_dwordx4 v[6:9], v[6:7], off
	s_waitcnt vmcnt(0)
	v_cvt_pk_f32_fp8_e32 v[10:11], v6
	v_cvt_pk_f32_fp8_sdwa v[12:13], v6 src0_sel:WORD_1
	v_cvt_pk_f32_fp8_e32 v[14:15], v7
	v_cvt_pk_f32_fp8_sdwa v[6:7], v7 src0_sel:WORD_1
	v_cvt_pk_f32_fp8_e32 v[30:31], v8
	v_cvt_pk_f32_fp8_sdwa v[32:33], v8 src0_sel:WORD_1
	v_cvt_pk_f32_fp8_e32 v[34:35], v9
	v_cvt_pk_f32_fp8_sdwa v[36:37], v9 src0_sel:WORD_1
	v_pk_fma_f32 v[22:23], v[16:17], v[10:11], 0 op_sel_hi:[0,1,0]
	v_pk_fma_f32 v[20:21], v[16:17], v[12:13], 0 op_sel_hi:[0,1,0]
	v_pk_fma_f32 v[18:19], v[16:17], v[14:15], 0 op_sel_hi:[0,1,0]
	v_pk_fma_f32 v[14:15], v[16:17], v[6:7], 0 op_sel_hi:[0,1,0]
	v_pk_fma_f32 v[12:13], v[16:17], v[30:31], 0 op_sel_hi:[0,1,0]
	v_pk_fma_f32 v[10:11], v[16:17], v[32:33], 0 op_sel_hi:[0,1,0]
	v_pk_fma_f32 v[8:9], v[16:17], v[34:35], 0 op_sel_hi:[0,1,0]
	v_pk_fma_f32 v[6:7], v[16:17], v[36:37], 0 op_sel_hi:[0,1,0]
	v_mov_b32_e32 v16, v28
